# P3/P5 epilogue row-sum reduction: ds_bpermute xor16/xor32 round trips replaced by v_permlane16_swap / v_permlane32_swap
# speedup vs baseline: 1.0067x; 1.0067x over previous
.LBB0_368:
	s_lshr_b64 s[0:1], s[36:37], 24
	s_lshl_b32 s6, s43, 5
	s_and_b32 s0, s0, 0xffffff00
	v_lshrrev_b32_e32 v100, 1, v164
	s_or_b32 s0, s6, s0
	s_lshl_b32 s23, s36, 8
	v_and_or_b32 v224, v100, 24, s0
	v_add_u32_e32 v222, s23, v237
	v_readlane_b32 s0, v254, 39
	v_ashrrev_i32_e32 v225, 31, v224
	v_readlane_b32 s1, v254, 40
	v_ashrrev_i32_e32 v223, 31, v222
	v_lshl_add_u64 v[102:103], v[222:223], 2, s[30:31]
	v_lshl_add_u64 v[100:101], v[224:225], 1, s[0:1]
	v_lshlrev_b64 v[226:227], 11, v[222:223]
	s_barrier
	v_lshl_add_u64 v[108:109], v[100:101], 0, v[226:227]
	global_load_dword v243, v[102:103], off
	global_load_dwordx4 v[204:207], v[108:109], off
	v_or_b32_e32 v102, 16, v222
	v_ashrrev_i32_e32 v103, 31, v102
	v_lshl_add_u64 v[110:111], v[102:103], 2, s[30:31]
	v_lshlrev_b64 v[102:103], 11, v[102:103]
	v_lshl_add_u64 v[102:103], v[100:101], 0, v[102:103]
	global_load_dwordx4 v[200:203], v[108:109], off offset:256
	global_load_dword v242, v[110:111], off
	global_load_dwordx4 v[196:199], v[102:103], off
	global_load_dwordx4 v[192:195], v[102:103], off offset:256
	v_or_b32_e32 v102, 32, v222
	v_ashrrev_i32_e32 v103, 31, v102
	v_lshl_add_u64 v[108:109], v[102:103], 2, s[30:31]
	v_lshlrev_b64 v[102:103], 11, v[102:103]
	v_lshl_add_u64 v[102:103], v[100:101], 0, v[102:103]
	global_load_dword v241, v[108:109], off
	global_load_dwordx4 v[188:191], v[102:103], off
	v_or_b32_e32 v108, 48, v222
	v_ashrrev_i32_e32 v109, 31, v108
	v_lshl_add_u64 v[110:111], v[108:109], 2, s[30:31]
	global_load_dwordx4 v[184:187], v[102:103], off offset:256
	global_load_dword v240, v[110:111], off
	v_lshlrev_b64 v[102:103], 11, v[108:109]
	v_lshl_add_u64 v[102:103], v[100:101], 0, v[102:103]
	global_load_dwordx4 v[172:175], v[102:103], off
	global_load_dwordx4 v[160:163], v[102:103], off offset:256
	v_add_u32_e32 v102, 0x80, v222
	v_ashrrev_i32_e32 v103, 31, v102
	v_lshl_add_u64 v[108:109], v[102:103], 2, s[30:31]
	v_lshlrev_b64 v[220:221], 11, v[102:103]
	v_lshl_add_u64 v[102:103], v[100:101], 0, v[220:221]
	global_load_dword v239, v[108:109], off
	global_load_dwordx4 v[148:151], v[102:103], off
	v_add_u32_e32 v108, 0x90, v222
	v_ashrrev_i32_e32 v109, 31, v108
	v_lshlrev_b64 v[218:219], 11, v[108:109]
	v_lshl_add_u64 v[110:111], v[108:109], 2, s[30:31]
	global_load_dwordx4 v[144:147], v[102:103], off offset:256
	global_load_dword v238, v[110:111], off
	v_lshl_add_u64 v[102:103], v[100:101], 0, v[218:219]
	global_load_dwordx4 v[132:135], v[102:103], off
	global_load_dwordx4 v[128:131], v[102:103], off offset:256
	v_add_u32_e32 v102, 0xa0, v222
	v_ashrrev_i32_e32 v103, 31, v102
	v_lshl_add_u64 v[108:109], v[102:103], 2, s[30:31]
	v_lshlrev_b64 v[216:217], 11, v[102:103]
	v_lshl_add_u64 v[102:103], v[100:101], 0, v[216:217]
	global_load_dword v236, v[108:109], off
	global_load_dwordx4 v[124:127], v[102:103], off
	v_add_u32_e32 v108, 0xb0, v222
	v_ashrrev_i32_e32 v109, 31, v108
	v_lshlrev_b64 v[214:215], 11, v[108:109]
	v_lshl_add_u64 v[110:111], v[108:109], 2, s[30:31]
	v_lshl_add_u64 v[100:101], v[100:101], 0, v[214:215]
	global_load_dwordx4 v[120:123], v[102:103], off offset:256
	global_load_dword v235, v[110:111], off
	s_nop 0
	global_load_dwordx4 v[108:111], v[100:101], off
	s_nop 0
	global_load_dwordx4 v[100:103], v[100:101], off offset:256
	v_and_b32_e32 v166, 64, v229
	v_xor_b32_e32 v165, 16, v229
	v_add_u32_e32 v166, 64, v166
	v_cmp_lt_i32_e32 vcc, v165, v166
	v_mul_f32_e32 v167, v159, v159
	v_fmac_f32_e32 v167, v158, v158
	v_cndmask_b32_e32 v165, v229, v165, vcc
	v_lshlrev_b32_e32 v223, 2, v165
	v_mul_f32_e32 v165, v157, v157
	v_fmac_f32_e32 v165, v156, v156
	v_add_f32_e32 v165, v165, v167
	v_mul_f32_e32 v167, v153, v153
	v_mul_f32_e32 v168, v155, v155
	v_fmac_f32_e32 v167, v152, v152
	v_fmac_f32_e32 v168, v154, v154
	v_add_f32_e32 v167, v167, v168
	v_add_f32_e32 v165, v165, v167
	v_mul_f32_e32 v167, v141, v141
	v_mul_f32_e32 v168, v143, v143
	v_fmac_f32_e32 v167, v140, v140
	v_fmac_f32_e32 v168, v142, v142
	v_add_f32_e32 v167, v167, v168
	v_add_f32_e32 v165, v165, v167
	v_mul_f32_e32 v167, v137, v137
	v_mul_f32_e32 v168, v139, v139
	v_fmac_f32_e32 v167, v136, v136
	v_fmac_f32_e32 v168, v138, v138
	v_add_f32_e32 v167, v167, v168
	v_add_f32_e32 v165, v165, v167
	v_mov_b32_e32 v167, v165
	s_nop 1
	v_permlane16_swap_b32_e32 v165, v167
	v_xor_b32_e32 v168, 32, v229
	v_cmp_lt_i32_e32 vcc, v168, v166
	v_and_b32_e32 v212, 63, v164
	s_lshl_b32 s0, s43, 2
	v_cndmask_b32_e32 v166, v229, v168, vcc
	v_lshlrev_b32_e32 v234, 2, v166
	s_waitcnt lgkmcnt(0)
	v_add_f32_e32 v165, v165, v167
	v_mov_b32_e32 v166, v165
	s_nop 1
	v_permlane32_swap_b32_e32 v165, v166
	v_cmp_gt_u32_e64 s[8:9], 16, v212
	s_add_i32 s43, s0, 0
	s_and_saveexec_b64 s[0:1], s[8:9]
	s_cbranch_execz .LBB0_370
	s_lshl_b32 s6, s42, 10
	s_add_i32 s6, s43, s6
	v_lshl_add_u32 v167, v233, 4, s6
	s_waitcnt lgkmcnt(0)
	v_add_f32_e32 v165, v165, v166
	ds_write_b32 v167, v165
.LBB0_370:
	s_or_b64 exec, exec, s[0:1]
	v_mul_f32_e32 v165, v117, v117
	s_waitcnt lgkmcnt(0)
	v_mul_f32_e32 v166, v119, v119
	v_fmac_f32_e32 v165, v116, v116
	v_fmac_f32_e32 v166, v118, v118
	v_add_f32_e32 v165, v165, v166
	v_mul_f32_e32 v166, v113, v113
	v_mul_f32_e32 v167, v115, v115
	v_fmac_f32_e32 v166, v112, v112
	v_fmac_f32_e32 v167, v114, v114
	v_add_f32_e32 v166, v166, v167
	v_add_f32_e32 v165, v165, v166
	v_mul_f32_e32 v166, v105, v105
	v_mul_f32_e32 v167, v107, v107
	v_fmac_f32_e32 v166, v104, v104
	v_fmac_f32_e32 v167, v106, v106
	v_add_f32_e32 v166, v166, v167
	v_add_f32_e32 v165, v165, v166
	v_mul_f32_e32 v166, v97, v97
	v_mul_f32_e32 v167, v99, v99
	v_fmac_f32_e32 v166, v96, v96
	v_fmac_f32_e32 v167, v98, v98
	v_add_f32_e32 v166, v166, v167
	v_add_f32_e32 v165, v165, v166
	v_mov_b32_e32 v166, v165
	s_nop 1
	v_permlane16_swap_b32_e32 v165, v166
	s_waitcnt lgkmcnt(0)
	v_add_f32_e32 v165, v165, v166
	v_mov_b32_e32 v166, v165
	s_nop 1
	v_permlane32_swap_b32_e32 v165, v166
	s_and_saveexec_b64 s[0:1], s[8:9]
	s_cbranch_execz .LBB0_372
	s_lshl_b32 s6, s42, 10
	s_add_i32 s6, s43, s6
	v_lshl_add_u32 v167, v233, 4, s6
	s_waitcnt lgkmcnt(0)
	v_add_f32_e32 v165, v165, v166
	ds_write_b32 v167, v165 offset:256
.LBB0_372:
	s_or_b64 exec, exec, s[0:1]
	v_mul_f32_e32 v165, v93, v93
	s_waitcnt lgkmcnt(0)
	v_mul_f32_e32 v166, v95, v95
	v_fmac_f32_e32 v165, v92, v92
	v_fmac_f32_e32 v166, v94, v94
	v_add_f32_e32 v165, v165, v166
	v_mul_f32_e32 v166, v89, v89
	v_mul_f32_e32 v167, v91, v91
	v_fmac_f32_e32 v166, v88, v88
	v_fmac_f32_e32 v167, v90, v90
	v_add_f32_e32 v166, v166, v167
	v_add_f32_e32 v165, v165, v166
	v_mul_f32_e32 v166, v85, v85
	v_mul_f32_e32 v167, v87, v87
	v_fmac_f32_e32 v166, v84, v84
	v_fmac_f32_e32 v167, v86, v86
	v_add_f32_e32 v166, v166, v167
	v_add_f32_e32 v165, v165, v166
	v_mul_f32_e32 v166, v81, v81
	v_mul_f32_e32 v167, v83, v83
	v_fmac_f32_e32 v166, v80, v80
	v_fmac_f32_e32 v167, v82, v82
	v_add_f32_e32 v166, v166, v167
	v_add_f32_e32 v165, v165, v166
	v_mov_b32_e32 v166, v165
	s_nop 1
	v_permlane16_swap_b32_e32 v165, v166
	s_waitcnt lgkmcnt(0)
	v_add_f32_e32 v165, v165, v166
	v_mov_b32_e32 v166, v165
	s_nop 1
	v_permlane32_swap_b32_e32 v165, v166
	s_and_saveexec_b64 s[0:1], s[8:9]
	s_cbranch_execz .LBB0_374
	s_lshl_b32 s6, s42, 10
	s_add_i32 s6, s43, s6
	v_lshl_add_u32 v167, v233, 4, s6
	s_waitcnt lgkmcnt(0)
	v_add_f32_e32 v165, v165, v166
	ds_write_b32 v167, v165 offset:512
.LBB0_374:
	s_or_b64 exec, exec, s[0:1]
	v_mul_f32_e32 v165, v77, v77
	s_waitcnt lgkmcnt(0)
	v_mul_f32_e32 v166, v79, v79
	v_fmac_f32_e32 v165, v76, v76
	v_fmac_f32_e32 v166, v78, v78
	v_add_f32_e32 v165, v165, v166
	v_mul_f32_e32 v166, v73, v73
	v_mul_f32_e32 v167, v75, v75
	v_fmac_f32_e32 v166, v72, v72
	v_fmac_f32_e32 v167, v74, v74
	v_add_f32_e32 v166, v166, v167
	v_add_f32_e32 v165, v165, v166
	v_mul_f32_e32 v166, v69, v69
	v_mul_f32_e32 v167, v71, v71
	v_fmac_f32_e32 v166, v68, v68
	v_fmac_f32_e32 v167, v70, v70
	v_add_f32_e32 v166, v166, v167
	v_add_f32_e32 v165, v165, v166
	v_mul_f32_e32 v166, v65, v65
	v_mul_f32_e32 v167, v67, v67
	v_fmac_f32_e32 v166, v64, v64
	v_fmac_f32_e32 v167, v66, v66
	v_add_f32_e32 v166, v166, v167
	v_add_f32_e32 v165, v165, v166
	v_mov_b32_e32 v166, v165
	s_nop 1
	v_permlane16_swap_b32_e32 v165, v166
	s_waitcnt lgkmcnt(0)
	v_add_f32_e32 v165, v165, v166
	v_mov_b32_e32 v166, v165
	s_nop 1
	v_permlane32_swap_b32_e32 v165, v166
	s_and_saveexec_b64 s[0:1], s[8:9]
	s_cbranch_execz .LBB0_376
	s_lshl_b32 s6, s42, 10
	s_add_i32 s6, s43, s6
	v_lshl_add_u32 v167, v233, 4, s6
	s_waitcnt lgkmcnt(0)
	v_add_f32_e32 v165, v165, v166
	ds_write_b32 v167, v165 offset:768
.LBB0_376:
	s_or_b64 exec, exec, s[0:1]
	v_mul_f32_e32 v165, v61, v61
	s_waitcnt lgkmcnt(0)
	v_mul_f32_e32 v166, v63, v63
	v_fmac_f32_e32 v165, v60, v60
	v_fmac_f32_e32 v166, v62, v62
	v_add_f32_e32 v165, v165, v166
	v_mul_f32_e32 v166, v57, v57
	v_mul_f32_e32 v167, v59, v59
	v_fmac_f32_e32 v166, v56, v56
	v_fmac_f32_e32 v167, v58, v58
	v_add_f32_e32 v166, v166, v167
	v_add_f32_e32 v165, v165, v166
	v_mul_f32_e32 v166, v53, v53
	v_mul_f32_e32 v167, v55, v55
	v_fmac_f32_e32 v166, v52, v52
	v_fmac_f32_e32 v167, v54, v54
	v_add_f32_e32 v166, v166, v167
	v_add_f32_e32 v165, v165, v166
	v_mul_f32_e32 v166, v49, v49
	v_mul_f32_e32 v167, v51, v51
	v_fmac_f32_e32 v166, v48, v48
	v_fmac_f32_e32 v167, v50, v50
	v_add_f32_e32 v166, v166, v167
	v_add_f32_e32 v165, v165, v166
	v_mov_b32_e32 v166, v165
	s_nop 1
	v_permlane16_swap_b32_e32 v165, v166
	s_waitcnt lgkmcnt(0)
	v_add_f32_e32 v165, v165, v166
	v_mov_b32_e32 v166, v165
	s_nop 1
	v_permlane32_swap_b32_e32 v165, v166
	s_and_saveexec_b64 s[0:1], s[8:9]
	s_cbranch_execz .LBB0_378
	s_lshl_b32 s6, s42, 10
	s_add_i32 s6, s43, s6
	v_lshl_add_u32 v167, v233, 4, s6
	s_waitcnt lgkmcnt(0)
	v_add_f32_e32 v165, v165, v166
	ds_write_b32 v167, v165 offset:2048
.LBB0_378:
	s_or_b64 exec, exec, s[0:1]
	v_mul_f32_e32 v165, v45, v45
	s_waitcnt lgkmcnt(0)
	v_mul_f32_e32 v166, v47, v47
	v_fmac_f32_e32 v165, v44, v44
	v_fmac_f32_e32 v166, v46, v46
	v_add_f32_e32 v165, v165, v166
	v_mul_f32_e32 v166, v41, v41
	v_mul_f32_e32 v167, v43, v43
	v_fmac_f32_e32 v166, v40, v40
	v_fmac_f32_e32 v167, v42, v42
	v_add_f32_e32 v166, v166, v167
	v_add_f32_e32 v165, v165, v166
	v_mul_f32_e32 v166, v37, v37
	v_mul_f32_e32 v167, v39, v39
	v_fmac_f32_e32 v166, v36, v36
	v_fmac_f32_e32 v167, v38, v38
	v_add_f32_e32 v166, v166, v167
	v_add_f32_e32 v165, v165, v166
	v_mul_f32_e32 v166, v33, v33
	v_mul_f32_e32 v167, v35, v35
	v_fmac_f32_e32 v166, v32, v32
	v_fmac_f32_e32 v167, v34, v34
	v_add_f32_e32 v166, v166, v167
	v_add_f32_e32 v165, v165, v166
	v_mov_b32_e32 v166, v165
	s_nop 1
	v_permlane16_swap_b32_e32 v165, v166
	s_waitcnt lgkmcnt(0)
	v_add_f32_e32 v165, v165, v166
	v_mov_b32_e32 v166, v165
	s_nop 1
	v_permlane32_swap_b32_e32 v165, v166
	s_and_saveexec_b64 s[0:1], s[8:9]
	s_cbranch_execz .LBB0_380
	s_lshl_b32 s6, s42, 10
	s_add_i32 s6, s43, s6
	v_lshl_add_u32 v167, v233, 4, s6
	s_waitcnt lgkmcnt(0)
	v_add_f32_e32 v165, v165, v166
	ds_write_b32 v167, v165 offset:2304
.LBB0_380:
	s_or_b64 exec, exec, s[0:1]
	v_mul_f32_e32 v165, v29, v29
	s_waitcnt lgkmcnt(0)
	v_mul_f32_e32 v166, v31, v31
	v_fmac_f32_e32 v165, v28, v28
	v_fmac_f32_e32 v166, v30, v30
	v_add_f32_e32 v165, v165, v166
	v_mul_f32_e32 v166, v25, v25
	v_mul_f32_e32 v167, v27, v27
	v_fmac_f32_e32 v166, v24, v24
	v_fmac_f32_e32 v167, v26, v26
	v_add_f32_e32 v166, v166, v167
	v_add_f32_e32 v165, v165, v166
	v_mul_f32_e32 v166, v21, v21
	v_mul_f32_e32 v167, v23, v23
	v_fmac_f32_e32 v166, v20, v20
	v_fmac_f32_e32 v167, v22, v22
	v_add_f32_e32 v166, v166, v167
	v_add_f32_e32 v165, v165, v166
	v_mul_f32_e32 v166, v17, v17
	v_mul_f32_e32 v167, v19, v19
	v_fmac_f32_e32 v166, v16, v16
	v_fmac_f32_e32 v167, v18, v18
	v_add_f32_e32 v166, v166, v167
	v_add_f32_e32 v165, v165, v166
	v_mov_b32_e32 v166, v165
	s_nop 1
	v_permlane16_swap_b32_e32 v165, v166
	s_waitcnt lgkmcnt(0)
	v_add_f32_e32 v165, v165, v166
	v_mov_b32_e32 v166, v165
	s_nop 1
	v_permlane32_swap_b32_e32 v165, v166
	s_and_saveexec_b64 s[0:1], s[8:9]
	s_cbranch_execz .LBB0_382
	s_lshl_b32 s6, s42, 10
	s_add_i32 s6, s43, s6
	v_lshl_add_u32 v167, v233, 4, s6
	s_waitcnt lgkmcnt(0)
	v_add_f32_e32 v165, v165, v166
	ds_write_b32 v167, v165 offset:2560
.LBB0_382:
	s_or_b64 exec, exec, s[0:1]
	v_mul_f32_e32 v165, v13, v13
	s_waitcnt lgkmcnt(0)
	v_mul_f32_e32 v166, v15, v15
	v_fmac_f32_e32 v165, v12, v12
	v_fmac_f32_e32 v166, v14, v14
	v_add_f32_e32 v165, v165, v166
	v_mul_f32_e32 v166, v9, v9
	v_mul_f32_e32 v167, v11, v11
	v_fmac_f32_e32 v166, v8, v8
	v_fmac_f32_e32 v167, v10, v10
	v_add_f32_e32 v166, v166, v167
	v_add_f32_e32 v165, v165, v166
	v_mul_f32_e32 v166, v5, v5
	v_mul_f32_e32 v167, v7, v7
	v_fmac_f32_e32 v166, v4, v4
	v_fmac_f32_e32 v167, v6, v6
	v_add_f32_e32 v166, v166, v167
	v_add_f32_e32 v165, v165, v166
	v_mul_f32_e32 v166, v1, v1
	v_mul_f32_e32 v167, v3, v3
	v_fmac_f32_e32 v166, v0, v0
	v_fmac_f32_e32 v167, v2, v2
	v_add_f32_e32 v166, v166, v167
	v_add_f32_e32 v165, v165, v166
	v_mov_b32_e32 v166, v165
	s_nop 1
	v_permlane16_swap_b32_e32 v165, v166
	s_waitcnt lgkmcnt(0)
	v_add_f32_e32 v165, v165, v166
	v_mov_b32_e32 v166, v165
	s_nop 1
	v_permlane32_swap_b32_e32 v165, v166
	s_and_saveexec_b64 s[0:1], s[8:9]
	s_cbranch_execz .LBB0_384
	s_lshl_b32 s6, s42, 10
	s_add_i32 s6, s43, s6
	v_lshl_add_u32 v167, v233, 4, s6
	s_waitcnt lgkmcnt(0)
	v_add_f32_e32 v165, v165, v166
	ds_write_b32 v167, v165 offset:2816

.LBB0_395:
	s_or_b64 exec, exec, s[26:27]
	s_waitcnt lgkmcnt(0)
	s_barrier
	v_lshl_add_u64 v[168:169], v[224:225], 2, s[74:75]
	global_load_dwordx4 v[176:179], v[168:169], off offset:16
	global_load_dwordx4 v[180:183], v[168:169], off
	global_load_dwordx4 v[164:167], v[168:169], off offset:528
	s_nop 0
	global_load_dwordx4 v[168:171], v[168:169], off offset:512
	s_waitcnt vmcnt(0)
	v_div_scale_f32 v244, s[10:11], v243, v243, 1.0
	v_rcp_f32_e32 v245, v244
	v_lshl_add_u32 v237, v237, 2, 0
	ds_read_b32 v248, v237 offset:4096
	v_fma_f32 v246, -v244, v245, 1.0
	v_fmac_f32_e32 v245, v246, v245
	v_div_scale_f32 v246, vcc, 1.0, v243, 1.0
	v_mul_f32_e32 v247, v246, v245
	v_fma_f32 v249, -v244, v247, v246
	v_fmac_f32_e32 v247, v249, v245
	v_fma_f32 v244, -v244, v247, v246
	v_div_fmas_f32 v244, v244, v245, v247
	s_waitcnt lgkmcnt(0)
	v_pk_mul_f32 v[158:159], v[158:159], v[248:249] op_sel_hi:[1,0]
	v_pk_mul_f32 v[154:155], v[154:155], v[248:249] op_sel_hi:[1,0]
	v_div_fixup_f32 v250, v244, v243, 1.0
	v_lshlrev_b32_e32 v244, 16, v204
	v_and_b32_e32 v245, 0xffff0000, v204
	v_lshlrev_b32_e32 v204, 16, v205
	v_and_b32_e32 v205, 0xffff0000, v205
	v_lshlrev_b32_e32 v246, 16, v206
	v_and_b32_e32 v247, 0xffff0000, v206
	v_lshlrev_b32_e32 v206, 16, v207
	v_and_b32_e32 v207, 0xffff0000, v207
	v_pk_mul_f32 v[142:143], v[142:143], v[248:249] op_sel_hi:[1,0]
	v_pk_mul_f32 v[140:141], v[140:141], v[248:249] op_sel_hi:[1,0]
	v_pk_mul_f32 v[138:139], v[138:139], v[248:249] op_sel_hi:[1,0]
	v_pk_mul_f32 v[136:137], v[136:137], v[248:249] op_sel_hi:[1,0]
	v_pk_mul_f32 v[156:157], v[156:157], v[248:249] op_sel_hi:[1,0]
	v_pk_mul_f32 v[152:153], v[152:153], v[248:249] op_sel_hi:[1,0]
	v_pk_mul_f32 v[154:155], v[178:179], v[154:155]
	v_pk_mul_f32 v[158:159], v[182:183], v[158:159]
	v_pk_fma_f32 v[154:155], v[250:251], v[206:207], v[154:155] op_sel_hi:[0,1,1]
	v_pk_fma_f32 v[158:159], v[250:251], v[204:205], v[158:159] op_sel_hi:[0,1,1]
	v_lshl_add_u64 v[206:207], s[16:17], 0, v[226:227]
	v_lshlrev_b64 v[204:205], 1, v[224:225]
	v_lshlrev_b32_e32 v224, 16, v200
	v_and_b32_e32 v225, 0xffff0000, v200
	v_lshlrev_b32_e32 v200, 16, v201
	v_and_b32_e32 v201, 0xffff0000, v201
	v_lshlrev_b32_e32 v226, 16, v202
	v_and_b32_e32 v227, 0xffff0000, v202
	v_lshlrev_b32_e32 v202, 16, v203
	v_and_b32_e32 v203, 0xffff0000, v203
	v_pk_mul_f32 v[140:141], v[168:169], v[140:141]
	v_pk_mul_f32 v[142:143], v[170:171], v[142:143]
	v_pk_mul_f32 v[136:137], v[164:165], v[136:137]
	v_pk_mul_f32 v[138:139], v[166:167], v[138:139]
	v_pk_fma_f32 v[142:143], v[250:251], v[200:201], v[142:143] op_sel_hi:[0,1,1]
	v_pk_fma_f32 v[140:141], v[250:251], v[224:225], v[140:141] op_sel_hi:[0,1,1]
	v_pk_fma_f32 v[138:139], v[250:251], v[202:203], v[138:139] op_sel_hi:[0,1,1]
	v_pk_fma_f32 v[136:137], v[250:251], v[226:227], v[136:137] op_sel_hi:[0,1,1]
	v_lshl_add_u64 v[206:207], v[206:207], 0, v[204:205]
	v_cvt_pk_bf16_f32 v200, v140, v141
	v_cvt_pk_bf16_f32 v201, v142, v143
	v_cvt_pk_bf16_f32 v202, v136, v137
	v_cvt_pk_bf16_f32 v203, v138, v139
	global_store_dwordx4 v[206:207], v[200:203], off offset:256
	v_pk_mul_f32 v[156:157], v[180:181], v[156:157]
	v_pk_mul_f32 v[152:153], v[176:177], v[152:153]
	v_div_scale_f32 v201, s[10:11], v242, v242, 1.0
	v_rcp_f32_e32 v202, v201
	v_pk_fma_f32 v[156:157], v[250:251], v[244:245], v[156:157] op_sel_hi:[0,1,1]
	v_pk_fma_f32 v[152:153], v[250:251], v[246:247], v[152:153] op_sel_hi:[0,1,1]
	v_cvt_pk_bf16_f32 v244, v156, v157
	v_fma_f32 v203, -v201, v202, 1.0
	v_cvt_pk_bf16_f32 v245, v158, v159
	v_cvt_pk_bf16_f32 v246, v152, v153
	v_cvt_pk_bf16_f32 v247, v154, v155
	v_fmac_f32_e32 v202, v203, v202
	v_div_scale_f32 v203, vcc, 1.0, v242, 1.0
	global_store_dwordx4 v[206:207], v[244:247], off
	ds_read_b32 v200, v237 offset:4160
	v_mul_f32_e32 v206, v203, v202
	v_fma_f32 v207, -v201, v206, v203
	v_fmac_f32_e32 v206, v207, v202
	v_fma_f32 v201, -v201, v206, v203
	v_div_fmas_f32 v201, v201, v202, v206
	s_waitcnt lgkmcnt(0)
	v_pk_mul_f32 v[116:117], v[116:117], v[200:201] op_sel_hi:[1,0]
	v_div_fixup_f32 v202, v201, v242, 1.0
	v_lshlrev_b32_e32 v206, 16, v196
	v_and_b32_e32 v207, 0xffff0000, v196
	v_pk_mul_f32 v[116:117], v[180:181], v[116:117]
	v_pk_mul_f32 v[118:119], v[118:119], v[200:201] op_sel_hi:[1,0]
	v_pk_fma_f32 v[116:117], v[202:203], v[206:207], v[116:117] op_sel_hi:[0,1,1]
	v_add_u32_e32 v206, 16, v222
	v_pk_mul_f32 v[114:115], v[114:115], v[200:201] op_sel_hi:[1,0]
	v_pk_mul_f32 v[112:113], v[112:113], v[200:201] op_sel_hi:[1,0]
	v_ashrrev_i32_e32 v207, 31, v206
	v_lshlrev_b32_e32 v196, 16, v197
	v_and_b32_e32 v197, 0xffff0000, v197
	v_lshlrev_b32_e32 v224, 16, v198
	v_and_b32_e32 v225, 0xffff0000, v198
	v_lshlrev_b32_e32 v198, 16, v199
	v_and_b32_e32 v199, 0xffff0000, v199
	v_pk_mul_f32 v[118:119], v[182:183], v[118:119]
	v_pk_mul_f32 v[112:113], v[176:177], v[112:113]
	v_pk_mul_f32 v[114:115], v[178:179], v[114:115]
	v_lshlrev_b64 v[206:207], 11, v[206:207]
	v_pk_fma_f32 v[118:119], v[202:203], v[196:197], v[118:119] op_sel_hi:[0,1,1]
	v_pk_fma_f32 v[114:115], v[202:203], v[198:199], v[114:115] op_sel_hi:[0,1,1]
	v_pk_fma_f32 v[112:113], v[202:203], v[224:225], v[112:113] op_sel_hi:[0,1,1]
	v_lshl_add_u64 v[206:207], s[16:17], 0, v[206:207]
	v_cvt_pk_bf16_f32 v196, v116, v117
	v_cvt_pk_bf16_f32 v197, v118, v119
	v_cvt_pk_bf16_f32 v198, v112, v113
	v_cvt_pk_bf16_f32 v199, v114, v115
	v_lshl_add_u64 v[206:207], v[206:207], 0, v[204:205]
	v_pk_mul_f32 v[106:107], v[106:107], v[200:201] op_sel_hi:[1,0]
	v_pk_mul_f32 v[104:105], v[104:105], v[200:201] op_sel_hi:[1,0]
	v_pk_mul_f32 v[98:99], v[98:99], v[200:201] op_sel_hi:[1,0]
	v_pk_mul_f32 v[96:97], v[96:97], v[200:201] op_sel_hi:[1,0]
	global_store_dwordx4 v[206:207], v[196:199], off
	v_pk_mul_f32 v[104:105], v[168:169], v[104:105]
	v_pk_mul_f32 v[106:107], v[170:171], v[106:107]
	v_lshlrev_b32_e32 v196, 16, v192
	v_and_b32_e32 v197, 0xffff0000, v192
	v_lshlrev_b32_e32 v192, 16, v193
	v_and_b32_e32 v193, 0xffff0000, v193
	v_lshlrev_b32_e32 v198, 16, v194
	v_and_b32_e32 v199, 0xffff0000, v194
	v_lshlrev_b32_e32 v194, 16, v195
	v_and_b32_e32 v195, 0xffff0000, v195
	v_pk_mul_f32 v[96:97], v[164:165], v[96:97]
	v_pk_mul_f32 v[98:99], v[166:167], v[98:99]
	v_pk_fma_f32 v[106:107], v[202:203], v[192:193], v[106:107] op_sel_hi:[0,1,1]
	v_pk_fma_f32 v[104:105], v[202:203], v[196:197], v[104:105] op_sel_hi:[0,1,1]
	v_pk_fma_f32 v[98:99], v[202:203], v[194:195], v[98:99] op_sel_hi:[0,1,1]
	v_pk_fma_f32 v[96:97], v[202:203], v[198:199], v[96:97] op_sel_hi:[0,1,1]
	v_cvt_pk_bf16_f32 v192, v104, v105
	v_cvt_pk_bf16_f32 v193, v106, v107
	v_cvt_pk_bf16_f32 v194, v96, v97
	v_cvt_pk_bf16_f32 v195, v98, v99
	global_store_dwordx4 v[206:207], v[192:195], off offset:256
	ds_read_b32 v192, v237 offset:4224
	v_lshlrev_b32_e32 v198, 16, v190
	v_div_scale_f32 v193, s[10:11], v241, v241, 1.0
	v_rcp_f32_e32 v194, v193
	v_and_b32_e32 v199, 0xffff0000, v190
	v_lshlrev_b32_e32 v190, 16, v191
	v_and_b32_e32 v191, 0xffff0000, v191
	v_fma_f32 v195, -v193, v194, 1.0
	v_fmac_f32_e32 v194, v195, v194
	v_div_scale_f32 v195, vcc, 1.0, v241, 1.0
	v_mul_f32_e32 v196, v195, v194
	v_fma_f32 v197, -v193, v196, v195
	v_fmac_f32_e32 v196, v197, v194
	v_fma_f32 v193, -v193, v196, v195
	v_div_fmas_f32 v193, v193, v194, v196
	s_waitcnt lgkmcnt(0)
	v_pk_mul_f32 v[92:93], v[92:93], v[192:193] op_sel_hi:[1,0]
	v_div_fixup_f32 v194, v193, v241, 1.0
	v_lshlrev_b32_e32 v196, 16, v188
	v_and_b32_e32 v197, 0xffff0000, v188
	v_pk_mul_f32 v[92:93], v[180:181], v[92:93]
	v_pk_mul_f32 v[94:95], v[94:95], v[192:193] op_sel_hi:[1,0]
	v_pk_fma_f32 v[92:93], v[194:195], v[196:197], v[92:93] op_sel_hi:[0,1,1]
	v_add_u32_e32 v196, 32, v222
	v_pk_mul_f32 v[90:91], v[90:91], v[192:193] op_sel_hi:[1,0]
	v_pk_mul_f32 v[88:89], v[88:89], v[192:193] op_sel_hi:[1,0]
	v_ashrrev_i32_e32 v197, 31, v196
	v_lshlrev_b32_e32 v188, 16, v189
	v_and_b32_e32 v189, 0xffff0000, v189
	v_pk_mul_f32 v[94:95], v[182:183], v[94:95]
	v_pk_mul_f32 v[88:89], v[176:177], v[88:89]
	v_pk_mul_f32 v[90:91], v[178:179], v[90:91]
	v_lshlrev_b64 v[196:197], 11, v[196:197]
	v_pk_fma_f32 v[94:95], v[194:195], v[188:189], v[94:95] op_sel_hi:[0,1,1]
	v_pk_fma_f32 v[90:91], v[194:195], v[190:191], v[90:91] op_sel_hi:[0,1,1]
	v_pk_fma_f32 v[88:89], v[194:195], v[198:199], v[88:89] op_sel_hi:[0,1,1]
	v_lshl_add_u64 v[196:197], s[16:17], 0, v[196:197]
	v_cvt_pk_bf16_f32 v188, v92, v93
	v_cvt_pk_bf16_f32 v189, v94, v95
	v_cvt_pk_bf16_f32 v190, v88, v89
	v_cvt_pk_bf16_f32 v191, v90, v91
	v_lshl_add_u64 v[196:197], v[196:197], 0, v[204:205]
	v_pk_mul_f32 v[86:87], v[86:87], v[192:193] op_sel_hi:[1,0]
	v_pk_mul_f32 v[84:85], v[84:85], v[192:193] op_sel_hi:[1,0]
	v_pk_mul_f32 v[82:83], v[82:83], v[192:193] op_sel_hi:[1,0]
	v_pk_mul_f32 v[80:81], v[80:81], v[192:193] op_sel_hi:[1,0]
	global_store_dwordx4 v[196:197], v[188:191], off
	v_pk_mul_f32 v[84:85], v[168:169], v[84:85]
	v_pk_mul_f32 v[86:87], v[170:171], v[86:87]
	v_lshlrev_b32_e32 v188, 16, v184
	v_and_b32_e32 v189, 0xffff0000, v184
	v_lshlrev_b32_e32 v184, 16, v185
	v_and_b32_e32 v185, 0xffff0000, v185
	v_lshlrev_b32_e32 v190, 16, v186
	v_and_b32_e32 v191, 0xffff0000, v186
	v_lshlrev_b32_e32 v186, 16, v187
	v_and_b32_e32 v187, 0xffff0000, v187
	v_pk_mul_f32 v[80:81], v[164:165], v[80:81]
	v_pk_mul_f32 v[82:83], v[166:167], v[82:83]
	v_pk_fma_f32 v[86:87], v[194:195], v[184:185], v[86:87] op_sel_hi:[0,1,1]
	v_pk_fma_f32 v[84:85], v[194:195], v[188:189], v[84:85] op_sel_hi:[0,1,1]
	v_pk_fma_f32 v[82:83], v[194:195], v[186:187], v[82:83] op_sel_hi:[0,1,1]
	v_pk_fma_f32 v[80:81], v[194:195], v[190:191], v[80:81] op_sel_hi:[0,1,1]
	v_cvt_pk_bf16_f32 v184, v84, v85
	v_cvt_pk_bf16_f32 v185, v86, v87
	v_cvt_pk_bf16_f32 v186, v80, v81
	v_cvt_pk_bf16_f32 v187, v82, v83
	global_store_dwordx4 v[196:197], v[184:187], off offset:256
	ds_read_b32 v184, v237 offset:4288
	v_lshlrev_b32_e32 v190, 16, v174
	v_div_scale_f32 v185, s[10:11], v240, v240, 1.0
	v_rcp_f32_e32 v186, v185
	v_and_b32_e32 v191, 0xffff0000, v174
	v_lshlrev_b32_e32 v174, 16, v175
	v_and_b32_e32 v175, 0xffff0000, v175
	v_fma_f32 v187, -v185, v186, 1.0
	v_fmac_f32_e32 v186, v187, v186
	v_div_scale_f32 v187, vcc, 1.0, v240, 1.0
	v_mul_f32_e32 v188, v187, v186
	v_fma_f32 v189, -v185, v188, v187
	v_fmac_f32_e32 v188, v189, v186
	v_fma_f32 v185, -v185, v188, v187
	v_div_fmas_f32 v185, v185, v186, v188
	s_waitcnt lgkmcnt(0)
	v_pk_mul_f32 v[76:77], v[76:77], v[184:185] op_sel_hi:[1,0]
	v_div_fixup_f32 v186, v185, v240, 1.0
	v_lshlrev_b32_e32 v188, 16, v172
	v_and_b32_e32 v189, 0xffff0000, v172
	v_pk_mul_f32 v[76:77], v[180:181], v[76:77]
	v_pk_mul_f32 v[78:79], v[78:79], v[184:185] op_sel_hi:[1,0]
	v_pk_fma_f32 v[76:77], v[186:187], v[188:189], v[76:77] op_sel_hi:[0,1,1]
	v_add_u32_e32 v188, 48, v222
	v_pk_mul_f32 v[74:75], v[74:75], v[184:185] op_sel_hi:[1,0]
	v_pk_mul_f32 v[72:73], v[72:73], v[184:185] op_sel_hi:[1,0]
	v_ashrrev_i32_e32 v189, 31, v188
	v_lshlrev_b32_e32 v172, 16, v173
	v_and_b32_e32 v173, 0xffff0000, v173
	v_pk_mul_f32 v[78:79], v[182:183], v[78:79]
	v_pk_mul_f32 v[72:73], v[176:177], v[72:73]
	v_pk_mul_f32 v[74:75], v[178:179], v[74:75]
	v_lshlrev_b64 v[188:189], 11, v[188:189]
	v_pk_fma_f32 v[78:79], v[186:187], v[172:173], v[78:79] op_sel_hi:[0,1,1]
	v_pk_fma_f32 v[74:75], v[186:187], v[174:175], v[74:75] op_sel_hi:[0,1,1]
	v_pk_fma_f32 v[72:73], v[186:187], v[190:191], v[72:73] op_sel_hi:[0,1,1]
	v_lshl_add_u64 v[188:189], s[16:17], 0, v[188:189]
	v_cvt_pk_bf16_f32 v172, v76, v77
	v_cvt_pk_bf16_f32 v173, v78, v79
	v_cvt_pk_bf16_f32 v174, v72, v73
	v_cvt_pk_bf16_f32 v175, v74, v75
	v_lshl_add_u64 v[188:189], v[188:189], 0, v[204:205]
	v_pk_mul_f32 v[70:71], v[70:71], v[184:185] op_sel_hi:[1,0]
	v_pk_mul_f32 v[68:69], v[68:69], v[184:185] op_sel_hi:[1,0]
	v_pk_mul_f32 v[66:67], v[66:67], v[184:185] op_sel_hi:[1,0]
	v_pk_mul_f32 v[64:65], v[64:65], v[184:185] op_sel_hi:[1,0]
	global_store_dwordx4 v[188:189], v[172:175], off
	v_pk_mul_f32 v[68:69], v[168:169], v[68:69]
	v_pk_mul_f32 v[70:71], v[170:171], v[70:71]
	v_lshlrev_b32_e32 v172, 16, v160
	v_and_b32_e32 v173, 0xffff0000, v160
	v_lshlrev_b32_e32 v160, 16, v161
	v_and_b32_e32 v161, 0xffff0000, v161
	v_lshlrev_b32_e32 v174, 16, v162
	v_and_b32_e32 v175, 0xffff0000, v162
	v_lshlrev_b32_e32 v162, 16, v163
	v_and_b32_e32 v163, 0xffff0000, v163
	v_pk_mul_f32 v[64:65], v[164:165], v[64:65]
	v_pk_mul_f32 v[66:67], v[166:167], v[66:67]
	v_pk_fma_f32 v[70:71], v[186:187], v[160:161], v[70:71] op_sel_hi:[0,1,1]
	v_pk_fma_f32 v[68:69], v[186:187], v[172:173], v[68:69] op_sel_hi:[0,1,1]
	v_pk_fma_f32 v[66:67], v[186:187], v[162:163], v[66:67] op_sel_hi:[0,1,1]
	v_pk_fma_f32 v[64:65], v[186:187], v[174:175], v[64:65] op_sel_hi:[0,1,1]
	v_cvt_pk_bf16_f32 v160, v68, v69
	v_cvt_pk_bf16_f32 v161, v70, v71
	v_cvt_pk_bf16_f32 v162, v64, v65
	v_cvt_pk_bf16_f32 v163, v66, v67
	global_store_dwordx4 v[188:189], v[160:163], off offset:256
	ds_read_b32 v160, v237 offset:4608
	v_lshlrev_b32_e32 v174, 16, v150
	v_div_scale_f32 v161, s[10:11], v239, v239, 1.0
	v_rcp_f32_e32 v162, v161
	v_and_b32_e32 v175, 0xffff0000, v150
	v_lshlrev_b32_e32 v150, 16, v151
	v_and_b32_e32 v151, 0xffff0000, v151
	v_fma_f32 v163, -v161, v162, 1.0
	v_fmac_f32_e32 v162, v163, v162
	v_div_scale_f32 v163, vcc, 1.0, v239, 1.0
	v_mul_f32_e32 v172, v163, v162
	v_fma_f32 v173, -v161, v172, v163
	v_fmac_f32_e32 v172, v173, v162
	v_fma_f32 v161, -v161, v172, v163
	v_div_fmas_f32 v161, v161, v162, v172
	s_waitcnt lgkmcnt(0)
	v_pk_mul_f32 v[62:63], v[62:63], v[160:161] op_sel_hi:[1,0]
	v_pk_mul_f32 v[60:61], v[60:61], v[160:161] op_sel_hi:[1,0]
	v_pk_mul_f32 v[58:59], v[58:59], v[160:161] op_sel_hi:[1,0]
	v_pk_mul_f32 v[56:57], v[56:57], v[160:161] op_sel_hi:[1,0]
	v_div_fixup_f32 v162, v161, v239, 1.0
	v_lshlrev_b32_e32 v172, 16, v148
	v_and_b32_e32 v173, 0xffff0000, v148
	v_lshlrev_b32_e32 v148, 16, v149
	v_and_b32_e32 v149, 0xffff0000, v149
	v_pk_mul_f32 v[60:61], v[180:181], v[60:61]
	v_pk_mul_f32 v[62:63], v[182:183], v[62:63]
	v_pk_mul_f32 v[56:57], v[176:177], v[56:57]
	v_pk_mul_f32 v[58:59], v[178:179], v[58:59]
	v_pk_fma_f32 v[62:63], v[162:163], v[148:149], v[62:63] op_sel_hi:[0,1,1]
	v_pk_fma_f32 v[60:61], v[162:163], v[172:173], v[60:61] op_sel_hi:[0,1,1]
	v_pk_fma_f32 v[58:59], v[162:163], v[150:151], v[58:59] op_sel_hi:[0,1,1]
	v_pk_fma_f32 v[56:57], v[162:163], v[174:175], v[56:57] op_sel_hi:[0,1,1]
	v_lshl_add_u64 v[172:173], s[16:17], 0, v[220:221]
	v_cvt_pk_bf16_f32 v148, v60, v61
	v_cvt_pk_bf16_f32 v149, v62, v63
	v_cvt_pk_bf16_f32 v150, v56, v57
	v_cvt_pk_bf16_f32 v151, v58, v59
	v_lshl_add_u64 v[172:173], v[172:173], 0, v[204:205]
	v_pk_mul_f32 v[54:55], v[54:55], v[160:161] op_sel_hi:[1,0]
	v_pk_mul_f32 v[52:53], v[52:53], v[160:161] op_sel_hi:[1,0]
	v_pk_mul_f32 v[50:51], v[50:51], v[160:161] op_sel_hi:[1,0]
	v_pk_mul_f32 v[48:49], v[48:49], v[160:161] op_sel_hi:[1,0]
	global_store_dwordx4 v[172:173], v[148:151], off
	v_pk_mul_f32 v[52:53], v[168:169], v[52:53]
	v_pk_mul_f32 v[54:55], v[170:171], v[54:55]
	v_lshlrev_b32_e32 v148, 16, v144
	v_and_b32_e32 v149, 0xffff0000, v144
	v_lshlrev_b32_e32 v144, 16, v145
	v_and_b32_e32 v145, 0xffff0000, v145
	v_lshlrev_b32_e32 v150, 16, v146
	v_and_b32_e32 v151, 0xffff0000, v146
	v_lshlrev_b32_e32 v146, 16, v147
	v_and_b32_e32 v147, 0xffff0000, v147
	v_pk_mul_f32 v[48:49], v[164:165], v[48:49]
	v_pk_mul_f32 v[50:51], v[166:167], v[50:51]
	v_pk_fma_f32 v[54:55], v[162:163], v[144:145], v[54:55] op_sel_hi:[0,1,1]
	v_pk_fma_f32 v[52:53], v[162:163], v[148:149], v[52:53] op_sel_hi:[0,1,1]
	v_pk_fma_f32 v[50:51], v[162:163], v[146:147], v[50:51] op_sel_hi:[0,1,1]
	v_pk_fma_f32 v[48:49], v[162:163], v[150:151], v[48:49] op_sel_hi:[0,1,1]
	v_cvt_pk_bf16_f32 v144, v52, v53
	v_cvt_pk_bf16_f32 v145, v54, v55
	v_cvt_pk_bf16_f32 v146, v48, v49
	v_cvt_pk_bf16_f32 v147, v50, v51
	global_store_dwordx4 v[172:173], v[144:147], off offset:256
	ds_read_b32 v144, v237 offset:4672
	v_lshlrev_b32_e32 v150, 16, v134
	v_div_scale_f32 v145, s[10:11], v238, v238, 1.0
	v_rcp_f32_e32 v146, v145
	v_and_b32_e32 v151, 0xffff0000, v134
	v_lshlrev_b32_e32 v134, 16, v135
	v_and_b32_e32 v135, 0xffff0000, v135
	v_fma_f32 v147, -v145, v146, 1.0
	v_fmac_f32_e32 v146, v147, v146
	v_div_scale_f32 v147, vcc, 1.0, v238, 1.0
	v_mul_f32_e32 v148, v147, v146
	v_fma_f32 v149, -v145, v148, v147
	v_fmac_f32_e32 v148, v149, v146
	v_fma_f32 v145, -v145, v148, v147
	v_div_fmas_f32 v145, v145, v146, v148
	s_waitcnt lgkmcnt(0)
	v_pk_mul_f32 v[46:47], v[46:47], v[144:145] op_sel_hi:[1,0]
	v_pk_mul_f32 v[44:45], v[44:45], v[144:145] op_sel_hi:[1,0]
	v_pk_mul_f32 v[42:43], v[42:43], v[144:145] op_sel_hi:[1,0]
	v_pk_mul_f32 v[40:41], v[40:41], v[144:145] op_sel_hi:[1,0]
	v_div_fixup_f32 v146, v145, v238, 1.0
	v_lshlrev_b32_e32 v148, 16, v132
	v_and_b32_e32 v149, 0xffff0000, v132
	v_lshlrev_b32_e32 v132, 16, v133
	v_and_b32_e32 v133, 0xffff0000, v133
	v_pk_mul_f32 v[44:45], v[180:181], v[44:45]
	v_pk_mul_f32 v[46:47], v[182:183], v[46:47]
	v_pk_mul_f32 v[40:41], v[176:177], v[40:41]
	v_pk_mul_f32 v[42:43], v[178:179], v[42:43]
	v_pk_fma_f32 v[46:47], v[146:147], v[132:133], v[46:47] op_sel_hi:[0,1,1]
	v_pk_fma_f32 v[44:45], v[146:147], v[148:149], v[44:45] op_sel_hi:[0,1,1]
	v_pk_fma_f32 v[42:43], v[146:147], v[134:135], v[42:43] op_sel_hi:[0,1,1]
	v_pk_fma_f32 v[40:41], v[146:147], v[150:151], v[40:41] op_sel_hi:[0,1,1]
	v_lshl_add_u64 v[148:149], s[16:17], 0, v[218:219]
	v_cvt_pk_bf16_f32 v132, v44, v45
	v_cvt_pk_bf16_f32 v133, v46, v47
	v_cvt_pk_bf16_f32 v134, v40, v41
	v_cvt_pk_bf16_f32 v135, v42, v43
	v_lshl_add_u64 v[148:149], v[148:149], 0, v[204:205]
	v_pk_mul_f32 v[38:39], v[38:39], v[144:145] op_sel_hi:[1,0]
	v_pk_mul_f32 v[36:37], v[36:37], v[144:145] op_sel_hi:[1,0]
	v_pk_mul_f32 v[34:35], v[34:35], v[144:145] op_sel_hi:[1,0]
	v_pk_mul_f32 v[32:33], v[32:33], v[144:145] op_sel_hi:[1,0]
	global_store_dwordx4 v[148:149], v[132:135], off
	v_pk_mul_f32 v[36:37], v[168:169], v[36:37]
	v_pk_mul_f32 v[38:39], v[170:171], v[38:39]
	v_lshlrev_b32_e32 v132, 16, v128
	v_and_b32_e32 v133, 0xffff0000, v128
	v_lshlrev_b32_e32 v128, 16, v129
	v_and_b32_e32 v129, 0xffff0000, v129
	v_lshlrev_b32_e32 v134, 16, v130
	v_and_b32_e32 v135, 0xffff0000, v130
	v_lshlrev_b32_e32 v130, 16, v131
	v_and_b32_e32 v131, 0xffff0000, v131
	v_pk_mul_f32 v[32:33], v[164:165], v[32:33]
	v_pk_mul_f32 v[34:35], v[166:167], v[34:35]
	v_pk_fma_f32 v[38:39], v[146:147], v[128:129], v[38:39] op_sel_hi:[0,1,1]
	v_pk_fma_f32 v[36:37], v[146:147], v[132:133], v[36:37] op_sel_hi:[0,1,1]
	v_pk_fma_f32 v[34:35], v[146:147], v[130:131], v[34:35] op_sel_hi:[0,1,1]
	v_pk_fma_f32 v[32:33], v[146:147], v[134:135], v[32:33] op_sel_hi:[0,1,1]
	v_cvt_pk_bf16_f32 v128, v36, v37
	v_cvt_pk_bf16_f32 v129, v38, v39
	v_cvt_pk_bf16_f32 v130, v32, v33
	v_cvt_pk_bf16_f32 v131, v34, v35
	global_store_dwordx4 v[148:149], v[128:131], off offset:256
	ds_read_b32 v128, v237 offset:4736
	v_lshlrev_b32_e32 v134, 16, v126
	v_div_scale_f32 v129, s[10:11], v236, v236, 1.0
	v_rcp_f32_e32 v130, v129
	v_and_b32_e32 v135, 0xffff0000, v126
	v_lshlrev_b32_e32 v126, 16, v127
	v_and_b32_e32 v127, 0xffff0000, v127
	v_fma_f32 v131, -v129, v130, 1.0
	v_fmac_f32_e32 v130, v131, v130
	v_div_scale_f32 v131, vcc, 1.0, v236, 1.0
	v_mul_f32_e32 v132, v131, v130
	v_fma_f32 v133, -v129, v132, v131
	v_fmac_f32_e32 v132, v133, v130
	v_fma_f32 v129, -v129, v132, v131
	v_div_fmas_f32 v129, v129, v130, v132
	s_waitcnt lgkmcnt(0)
	v_pk_mul_f32 v[30:31], v[30:31], v[128:129] op_sel_hi:[1,0]
	v_pk_mul_f32 v[28:29], v[28:29], v[128:129] op_sel_hi:[1,0]
	v_pk_mul_f32 v[26:27], v[26:27], v[128:129] op_sel_hi:[1,0]
	v_pk_mul_f32 v[24:25], v[24:25], v[128:129] op_sel_hi:[1,0]
	v_div_fixup_f32 v130, v129, v236, 1.0
	v_lshlrev_b32_e32 v132, 16, v124
	v_and_b32_e32 v133, 0xffff0000, v124
	v_lshlrev_b32_e32 v124, 16, v125
	v_and_b32_e32 v125, 0xffff0000, v125
	v_pk_mul_f32 v[28:29], v[180:181], v[28:29]
	v_pk_mul_f32 v[30:31], v[182:183], v[30:31]
	v_pk_mul_f32 v[24:25], v[176:177], v[24:25]
	v_pk_mul_f32 v[26:27], v[178:179], v[26:27]
	v_pk_fma_f32 v[30:31], v[130:131], v[124:125], v[30:31] op_sel_hi:[0,1,1]
	v_pk_fma_f32 v[28:29], v[130:131], v[132:133], v[28:29] op_sel_hi:[0,1,1]
	v_pk_fma_f32 v[26:27], v[130:131], v[126:127], v[26:27] op_sel_hi:[0,1,1]
	v_pk_fma_f32 v[24:25], v[130:131], v[134:135], v[24:25] op_sel_hi:[0,1,1]
	v_lshl_add_u64 v[132:133], s[16:17], 0, v[216:217]
	v_cvt_pk_bf16_f32 v124, v28, v29
	v_cvt_pk_bf16_f32 v125, v30, v31
	v_cvt_pk_bf16_f32 v126, v24, v25
	v_cvt_pk_bf16_f32 v127, v26, v27
	v_lshl_add_u64 v[132:133], v[132:133], 0, v[204:205]
	v_pk_mul_f32 v[22:23], v[22:23], v[128:129] op_sel_hi:[1,0]
	v_pk_mul_f32 v[20:21], v[20:21], v[128:129] op_sel_hi:[1,0]
	v_pk_mul_f32 v[18:19], v[18:19], v[128:129] op_sel_hi:[1,0]
	v_pk_mul_f32 v[16:17], v[16:17], v[128:129] op_sel_hi:[1,0]
	global_store_dwordx4 v[132:133], v[124:127], off
	v_pk_mul_f32 v[20:21], v[168:169], v[20:21]
	v_pk_mul_f32 v[22:23], v[170:171], v[22:23]
	v_lshlrev_b32_e32 v124, 16, v120
	v_and_b32_e32 v125, 0xffff0000, v120
	v_lshlrev_b32_e32 v120, 16, v121
	v_and_b32_e32 v121, 0xffff0000, v121
	v_lshlrev_b32_e32 v126, 16, v122
	v_and_b32_e32 v127, 0xffff0000, v122
	v_lshlrev_b32_e32 v122, 16, v123
	v_and_b32_e32 v123, 0xffff0000, v123
	v_pk_mul_f32 v[16:17], v[164:165], v[16:17]
	v_pk_mul_f32 v[18:19], v[166:167], v[18:19]
	v_pk_fma_f32 v[22:23], v[130:131], v[120:121], v[22:23] op_sel_hi:[0,1,1]
	v_pk_fma_f32 v[20:21], v[130:131], v[124:125], v[20:21] op_sel_hi:[0,1,1]
	v_pk_fma_f32 v[18:19], v[130:131], v[122:123], v[18:19] op_sel_hi:[0,1,1]
	v_pk_fma_f32 v[16:17], v[130:131], v[126:127], v[16:17] op_sel_hi:[0,1,1]
	v_cvt_pk_bf16_f32 v120, v20, v21
	v_cvt_pk_bf16_f32 v121, v22, v23
	v_cvt_pk_bf16_f32 v122, v16, v17
	v_cvt_pk_bf16_f32 v123, v18, v19
	global_store_dwordx4 v[132:133], v[120:123], off offset:256
	ds_read_b32 v120, v237 offset:4800
	v_lshlrev_b32_e32 v126, 16, v110
	v_div_scale_f32 v121, s[10:11], v235, v235, 1.0
	v_rcp_f32_e32 v122, v121
	v_and_b32_e32 v127, 0xffff0000, v110
	v_lshlrev_b32_e32 v110, 16, v111
	v_and_b32_e32 v111, 0xffff0000, v111
	v_fma_f32 v123, -v121, v122, 1.0
	v_fmac_f32_e32 v122, v123, v122
	v_div_scale_f32 v123, vcc, 1.0, v235, 1.0
	v_mul_f32_e32 v124, v123, v122
	v_fma_f32 v125, -v121, v124, v123
	v_fmac_f32_e32 v124, v125, v122
	v_fma_f32 v121, -v121, v124, v123
	v_div_fmas_f32 v121, v121, v122, v124
	s_waitcnt lgkmcnt(0)
	v_pk_mul_f32 v[14:15], v[14:15], v[120:121] op_sel_hi:[1,0]
	v_pk_mul_f32 v[12:13], v[12:13], v[120:121] op_sel_hi:[1,0]
	v_pk_mul_f32 v[10:11], v[10:11], v[120:121] op_sel_hi:[1,0]
	v_pk_mul_f32 v[8:9], v[8:9], v[120:121] op_sel_hi:[1,0]
	v_div_fixup_f32 v122, v121, v235, 1.0
	v_lshlrev_b32_e32 v124, 16, v108
	v_and_b32_e32 v125, 0xffff0000, v108
	v_lshlrev_b32_e32 v108, 16, v109
	v_and_b32_e32 v109, 0xffff0000, v109
	v_pk_mul_f32 v[12:13], v[180:181], v[12:13]
	v_pk_mul_f32 v[14:15], v[182:183], v[14:15]
	v_pk_mul_f32 v[8:9], v[176:177], v[8:9]
	v_pk_mul_f32 v[10:11], v[178:179], v[10:11]
	v_pk_fma_f32 v[14:15], v[122:123], v[108:109], v[14:15] op_sel_hi:[0,1,1]
	v_pk_fma_f32 v[12:13], v[122:123], v[124:125], v[12:13] op_sel_hi:[0,1,1]
	v_pk_fma_f32 v[10:11], v[122:123], v[110:111], v[10:11] op_sel_hi:[0,1,1]
	v_pk_fma_f32 v[8:9], v[122:123], v[126:127], v[8:9] op_sel_hi:[0,1,1]
	v_lshl_add_u64 v[124:125], s[16:17], 0, v[214:215]
	v_cvt_pk_bf16_f32 v108, v12, v13
	v_cvt_pk_bf16_f32 v109, v14, v15
	v_cvt_pk_bf16_f32 v110, v8, v9
	v_cvt_pk_bf16_f32 v111, v10, v11
	v_lshl_add_u64 v[124:125], v[124:125], 0, v[204:205]
	v_pk_mul_f32 v[6:7], v[6:7], v[120:121] op_sel_hi:[1,0]
	v_pk_mul_f32 v[4:5], v[4:5], v[120:121] op_sel_hi:[1,0]
	v_pk_mul_f32 v[2:3], v[2:3], v[120:121] op_sel_hi:[1,0]
	v_pk_mul_f32 v[0:1], v[0:1], v[120:121] op_sel_hi:[1,0]
	global_store_dwordx4 v[124:125], v[108:111], off
	v_pk_mul_f32 v[4:5], v[168:169], v[4:5]
	v_pk_mul_f32 v[6:7], v[170:171], v[6:7]
	v_lshlrev_b32_e32 v108, 16, v100
	v_and_b32_e32 v109, 0xffff0000, v100
	v_lshlrev_b32_e32 v100, 16, v101
	v_and_b32_e32 v101, 0xffff0000, v101
	v_lshlrev_b32_e32 v110, 16, v102
	v_and_b32_e32 v111, 0xffff0000, v102
	v_lshlrev_b32_e32 v102, 16, v103
	v_and_b32_e32 v103, 0xffff0000, v103
	v_pk_mul_f32 v[0:1], v[164:165], v[0:1]
	v_pk_mul_f32 v[2:3], v[166:167], v[2:3]
	v_pk_fma_f32 v[6:7], v[122:123], v[100:101], v[6:7] op_sel_hi:[0,1,1]
	v_pk_fma_f32 v[4:5], v[122:123], v[108:109], v[4:5] op_sel_hi:[0,1,1]
	v_pk_fma_f32 v[2:3], v[122:123], v[102:103], v[2:3] op_sel_hi:[0,1,1]
	v_pk_fma_f32 v[0:1], v[122:123], v[110:111], v[0:1] op_sel_hi:[0,1,1]
	v_cvt_pk_bf16_f32 v100, v4, v5
	v_cvt_pk_bf16_f32 v101, v6, v7
	v_cvt_pk_bf16_f32 v102, v0, v1
	v_cvt_pk_bf16_f32 v103, v2, v3
	global_store_dwordx4 v[124:125], v[100:103], off offset:256
	s_nop 1
	v_mul_f32_e32 v100, v157, v157
	v_mul_f32_e32 v101, v159, v159
	v_fmac_f32_e32 v100, v156, v156
	v_fmac_f32_e32 v101, v158, v158
	v_add_f32_e32 v100, v100, v101
	v_mul_f32_e32 v101, v153, v153
	v_mul_f32_e32 v102, v155, v155
	v_fmac_f32_e32 v101, v152, v152
	v_fmac_f32_e32 v102, v154, v154
	v_add_f32_e32 v101, v101, v102
	v_add_f32_e32 v100, v100, v101
	v_mul_f32_e32 v101, v141, v141
	v_mul_f32_e32 v102, v143, v143
	v_fmac_f32_e32 v101, v140, v140
	v_fmac_f32_e32 v102, v142, v142
	v_add_f32_e32 v101, v101, v102
	v_add_f32_e32 v100, v101, v100
	v_mul_f32_e32 v101, v137, v137
	v_mul_f32_e32 v102, v139, v139
	v_fmac_f32_e32 v101, v136, v136
	v_fmac_f32_e32 v102, v138, v138
	v_add_f32_e32 v101, v101, v102
	v_add_f32_e32 v100, v101, v100
	v_mov_b32_e32 v101, v100
	s_nop 1
	v_permlane16_swap_b32_e32 v100, v101
	s_waitcnt lgkmcnt(0)
	v_add_f32_e32 v100, v100, v101
	v_mov_b32_e32 v101, v100
	s_nop 1
	v_permlane32_swap_b32_e32 v100, v101
	s_and_saveexec_b64 s[10:11], s[8:9]
	s_cbranch_execz .LBB0_397
	s_lshl_b32 s26, s42, 10
	s_add_i32 s26, s43, s26
	v_lshl_add_u32 v102, v233, 4, s26
	s_waitcnt lgkmcnt(0)
	v_add_f32_e32 v100, v100, v101
	ds_write_b32 v102, v100 offset:8192
.LBB0_397:
	s_or_b64 exec, exec, s[10:11]
	v_mul_f32_e32 v100, v117, v117
	s_waitcnt lgkmcnt(0)
	v_mul_f32_e32 v101, v119, v119
	v_fmac_f32_e32 v100, v116, v116
	v_fmac_f32_e32 v101, v118, v118
	v_add_f32_e32 v100, v100, v101
	v_mul_f32_e32 v101, v113, v113
	v_mul_f32_e32 v102, v115, v115
	v_fmac_f32_e32 v101, v112, v112
	v_fmac_f32_e32 v102, v114, v114
	v_add_f32_e32 v101, v101, v102
	v_add_f32_e32 v100, v100, v101
	v_mul_f32_e32 v101, v105, v105
	v_mul_f32_e32 v102, v107, v107
	v_mul_f32_e32 v97, v97, v97
	v_fmac_f32_e32 v101, v104, v104
	v_fmac_f32_e32 v102, v106, v106
	v_fmac_f32_e32 v97, v96, v96
	v_mul_f32_e32 v96, v99, v99
	v_add_f32_e32 v101, v101, v102
	v_fmac_f32_e32 v96, v98, v98
	v_add_f32_e32 v100, v101, v100
	v_add_f32_e32 v96, v97, v96
	v_add_f32_e32 v96, v96, v100
	v_mov_b32_e32 v97, v96
	s_nop 1
	v_permlane16_swap_b32_e32 v96, v97
	s_waitcnt lgkmcnt(0)
	v_add_f32_e32 v96, v96, v97
	v_mov_b32_e32 v97, v96
	s_nop 1
	v_permlane32_swap_b32_e32 v96, v97
	s_and_saveexec_b64 s[10:11], s[8:9]
	s_cbranch_execz .LBB0_399
	s_lshl_b32 s26, s42, 10
	s_add_i32 s26, s43, s26
	v_lshl_add_u32 v98, v233, 4, s26
	s_waitcnt lgkmcnt(0)
	v_add_f32_e32 v96, v96, v97
	ds_write_b32 v98, v96 offset:8448
.LBB0_399:
	s_or_b64 exec, exec, s[10:11]
	v_mul_f32_e32 v93, v93, v93
	v_mul_f32_e32 v89, v89, v89
	v_fmac_f32_e32 v93, v92, v92
	v_mul_f32_e32 v92, v95, v95
	v_fmac_f32_e32 v89, v88, v88
	v_mul_f32_e32 v88, v91, v91
	v_mul_f32_e32 v85, v85, v85
	v_fmac_f32_e32 v92, v94, v94
	v_fmac_f32_e32 v88, v90, v90
	v_fmac_f32_e32 v85, v84, v84
	v_mul_f32_e32 v84, v87, v87
	v_mul_f32_e32 v81, v81, v81
	v_add_f32_e32 v92, v93, v92
	v_add_f32_e32 v88, v89, v88
	v_fmac_f32_e32 v84, v86, v86
	v_fmac_f32_e32 v81, v80, v80
	v_mul_f32_e32 v80, v83, v83
	v_add_f32_e32 v88, v92, v88
	v_add_f32_e32 v84, v85, v84
	v_fmac_f32_e32 v80, v82, v82
	v_add_f32_e32 v84, v84, v88
	v_add_f32_e32 v80, v81, v80
	v_add_f32_e32 v80, v80, v84
	v_mov_b32_e32 v81, v80
	s_nop 1
	v_permlane16_swap_b32_e32 v80, v81
	s_waitcnt lgkmcnt(0)
	v_add_f32_e32 v80, v80, v81
	v_mov_b32_e32 v81, v80
	s_nop 1
	v_permlane32_swap_b32_e32 v80, v81
	s_and_saveexec_b64 s[10:11], s[8:9]
	s_cbranch_execz .LBB0_401
	s_lshl_b32 s26, s42, 10
	s_add_i32 s26, s43, s26
	v_lshl_add_u32 v82, v233, 4, s26
	s_waitcnt lgkmcnt(0)
	v_add_f32_e32 v80, v80, v81
	ds_write_b32 v82, v80 offset:8704
.LBB0_401:
	s_or_b64 exec, exec, s[10:11]
	v_mul_f32_e32 v77, v77, v77
	v_mul_f32_e32 v73, v73, v73
	v_fmac_f32_e32 v77, v76, v76
	v_mul_f32_e32 v76, v79, v79
	v_fmac_f32_e32 v73, v72, v72
	v_mul_f32_e32 v72, v75, v75
	v_mul_f32_e32 v69, v69, v69
	v_fmac_f32_e32 v76, v78, v78
	v_fmac_f32_e32 v72, v74, v74
	v_fmac_f32_e32 v69, v68, v68
	v_mul_f32_e32 v68, v71, v71
	v_mul_f32_e32 v65, v65, v65
	v_add_f32_e32 v76, v77, v76
	v_add_f32_e32 v72, v73, v72
	v_fmac_f32_e32 v68, v70, v70
	v_fmac_f32_e32 v65, v64, v64
	v_mul_f32_e32 v64, v67, v67
	v_add_f32_e32 v72, v76, v72
	v_add_f32_e32 v68, v69, v68
	v_fmac_f32_e32 v64, v66, v66
	v_add_f32_e32 v68, v68, v72
	v_add_f32_e32 v64, v65, v64
	v_add_f32_e32 v64, v64, v68
	v_mov_b32_e32 v65, v64
	s_nop 1
	v_permlane16_swap_b32_e32 v64, v65
	s_waitcnt lgkmcnt(0)
	v_add_f32_e32 v64, v64, v65
	v_mov_b32_e32 v65, v64
	s_nop 1
	v_permlane32_swap_b32_e32 v64, v65
	s_and_saveexec_b64 s[10:11], s[8:9]
	s_cbranch_execz .LBB0_403
	s_lshl_b32 s26, s42, 10
	s_add_i32 s26, s43, s26
	v_lshl_add_u32 v66, v233, 4, s26
	s_waitcnt lgkmcnt(0)
	v_add_f32_e32 v64, v64, v65
	ds_write_b32 v66, v64 offset:8960
.LBB0_403:
	s_or_b64 exec, exec, s[10:11]
	v_mul_f32_e32 v61, v61, v61
	v_mul_f32_e32 v57, v57, v57
	v_fmac_f32_e32 v61, v60, v60
	v_mul_f32_e32 v60, v63, v63
	v_fmac_f32_e32 v57, v56, v56
	v_mul_f32_e32 v56, v59, v59
	v_mul_f32_e32 v53, v53, v53
	v_fmac_f32_e32 v60, v62, v62
	v_fmac_f32_e32 v56, v58, v58
	v_fmac_f32_e32 v53, v52, v52
	v_mul_f32_e32 v52, v55, v55
	v_mul_f32_e32 v49, v49, v49
	v_add_f32_e32 v60, v61, v60
	v_add_f32_e32 v56, v57, v56
	v_fmac_f32_e32 v52, v54, v54
	v_fmac_f32_e32 v49, v48, v48
	v_mul_f32_e32 v48, v51, v51
	v_add_f32_e32 v56, v60, v56
	v_add_f32_e32 v52, v53, v52
	v_fmac_f32_e32 v48, v50, v50
	v_add_f32_e32 v52, v52, v56
	v_add_f32_e32 v48, v49, v48
	v_add_f32_e32 v48, v48, v52
	v_mov_b32_e32 v49, v48
	s_nop 1
	v_permlane16_swap_b32_e32 v48, v49
	s_waitcnt lgkmcnt(0)
	v_add_f32_e32 v48, v48, v49
	v_mov_b32_e32 v49, v48
	s_nop 1
	v_permlane32_swap_b32_e32 v48, v49
	s_and_saveexec_b64 s[10:11], s[8:9]
	s_cbranch_execz .LBB0_405
	s_lshl_b32 s26, s42, 10
	s_add_i32 s26, s43, s26
	v_lshl_add_u32 v50, v233, 4, s26
	s_waitcnt lgkmcnt(0)
	v_add_f32_e32 v48, v48, v49
	ds_write_b32 v50, v48 offset:10240
.LBB0_405:
	s_or_b64 exec, exec, s[10:11]
	v_mul_f32_e32 v45, v45, v45
	v_mul_f32_e32 v41, v41, v41
	v_fmac_f32_e32 v45, v44, v44
	v_mul_f32_e32 v44, v47, v47
	v_fmac_f32_e32 v41, v40, v40
	v_mul_f32_e32 v40, v43, v43
	v_mul_f32_e32 v37, v37, v37
	v_fmac_f32_e32 v44, v46, v46
	v_fmac_f32_e32 v40, v42, v42
	v_fmac_f32_e32 v37, v36, v36
	v_mul_f32_e32 v36, v39, v39
	v_mul_f32_e32 v33, v33, v33
	v_add_f32_e32 v44, v45, v44
	v_add_f32_e32 v40, v41, v40
	v_fmac_f32_e32 v36, v38, v38
	v_fmac_f32_e32 v33, v32, v32
	v_mul_f32_e32 v32, v35, v35
	v_add_f32_e32 v40, v44, v40
	v_add_f32_e32 v36, v37, v36
	v_fmac_f32_e32 v32, v34, v34
	v_add_f32_e32 v36, v36, v40
	v_add_f32_e32 v32, v33, v32
	v_add_f32_e32 v32, v32, v36
	v_mov_b32_e32 v33, v32
	s_nop 1
	v_permlane16_swap_b32_e32 v32, v33
	s_waitcnt lgkmcnt(0)
	v_add_f32_e32 v32, v32, v33
	v_mov_b32_e32 v33, v32
	s_nop 1
	v_permlane32_swap_b32_e32 v32, v33
	s_and_saveexec_b64 s[10:11], s[8:9]
	s_cbranch_execz .LBB0_407
	s_lshl_b32 s26, s42, 10
	s_add_i32 s26, s43, s26
	v_lshl_add_u32 v34, v233, 4, s26
	s_waitcnt lgkmcnt(0)
	v_add_f32_e32 v32, v32, v33
	ds_write_b32 v34, v32 offset:10496
.LBB0_407:
	s_or_b64 exec, exec, s[10:11]
	v_mul_f32_e32 v29, v29, v29
	v_mul_f32_e32 v25, v25, v25
	v_fmac_f32_e32 v29, v28, v28
	v_mul_f32_e32 v28, v31, v31
	v_fmac_f32_e32 v25, v24, v24
	v_mul_f32_e32 v24, v27, v27
	v_mul_f32_e32 v21, v21, v21
	v_fmac_f32_e32 v28, v30, v30
	v_fmac_f32_e32 v24, v26, v26
	v_fmac_f32_e32 v21, v20, v20
	v_mul_f32_e32 v20, v23, v23
	v_mul_f32_e32 v17, v17, v17
	v_add_f32_e32 v28, v29, v28
	v_add_f32_e32 v24, v25, v24
	v_fmac_f32_e32 v20, v22, v22
	v_fmac_f32_e32 v17, v16, v16
	v_mul_f32_e32 v16, v19, v19
	v_add_f32_e32 v24, v28, v24
	v_add_f32_e32 v20, v21, v20
	v_fmac_f32_e32 v16, v18, v18
	v_add_f32_e32 v20, v20, v24
	v_add_f32_e32 v16, v17, v16
	v_add_f32_e32 v16, v16, v20
	v_mov_b32_e32 v17, v16
	s_nop 1
	v_permlane16_swap_b32_e32 v16, v17
	s_waitcnt lgkmcnt(0)
	v_add_f32_e32 v16, v16, v17
	v_mov_b32_e32 v17, v16
	s_nop 1
	v_permlane32_swap_b32_e32 v16, v17
	s_and_saveexec_b64 s[10:11], s[8:9]
	s_cbranch_execz .LBB0_409
	s_lshl_b32 s26, s42, 10
	s_add_i32 s26, s43, s26
	v_lshl_add_u32 v18, v233, 4, s26
	s_waitcnt lgkmcnt(0)
	v_add_f32_e32 v16, v16, v17
	ds_write_b32 v18, v16 offset:10752
.LBB0_409:
	s_or_b64 exec, exec, s[10:11]
	v_mul_f32_e32 v13, v13, v13
	v_mul_f32_e32 v9, v9, v9
	v_fmac_f32_e32 v13, v12, v12
	v_mul_f32_e32 v12, v15, v15
	v_fmac_f32_e32 v9, v8, v8
	v_mul_f32_e32 v8, v11, v11
	v_mul_f32_e32 v5, v5, v5
	v_fmac_f32_e32 v12, v14, v14
	v_fmac_f32_e32 v8, v10, v10
	v_fmac_f32_e32 v5, v4, v4
	v_mul_f32_e32 v4, v7, v7
	v_mul_f32_e32 v1, v1, v1
	v_add_f32_e32 v12, v13, v12
	v_add_f32_e32 v8, v9, v8
	v_fmac_f32_e32 v4, v6, v6
	v_fmac_f32_e32 v1, v0, v0
	v_mul_f32_e32 v0, v3, v3
	v_add_f32_e32 v8, v12, v8
	v_add_f32_e32 v4, v5, v4
	v_fmac_f32_e32 v0, v2, v2
	v_add_f32_e32 v4, v4, v8
	v_add_f32_e32 v0, v1, v0
	v_add_f32_e32 v0, v0, v4
	v_mov_b32_e32 v1, v0
	s_nop 1
	v_permlane16_swap_b32_e32 v0, v1
	s_waitcnt lgkmcnt(0)
	v_add_f32_e32 v0, v0, v1
	v_mov_b32_e32 v1, v0
	s_nop 1
	v_permlane32_swap_b32_e32 v0, v1
	s_and_saveexec_b64 s[10:11], s[8:9]
	s_cbranch_execz .LBB0_411
	s_lshl_b32 s8, s42, 10
	s_add_i32 s43, s43, s8
	v_lshl_add_u32 v2, v233, 4, s43
	s_waitcnt lgkmcnt(0)
	v_add_f32_e32 v0, v0, v1
	ds_write_b32 v2, v0 offset:11008

.LBB0_602:
	s_lshr_b64 s[0:1], s[6:7], 24
	s_lshl_b32 s10, s3, 5
	s_and_b32 s0, s0, 0xffffff00
	s_lshl_b32 s18, s6, 8
	v_lshrrev_b32_e32 v128, 1, v182
	s_or_b32 s0, s10, s0
	s_add_i32 s47, s47, s18
	v_and_or_b32 v180, v128, 24, s0
	v_or_b32_e32 v128, s47, v183
	v_ashrrev_i32_e32 v181, 31, v180
	v_ashrrev_i32_e32 v129, 31, v128
	v_lshl_add_u64 v[130:131], v[180:181], 1, s[16:17]
	v_lshlrev_b64 v[132:133], 11, v[128:129]
	v_lshl_add_u64 v[132:133], v[130:131], 0, v[132:133]
	s_barrier
	global_load_dwordx4 v[204:207], v[132:133], off
	global_load_dwordx4 v[196:199], v[132:133], off offset:256
	v_or_b32_e32 v132, 16, v128
	v_ashrrev_i32_e32 v133, 31, v132
	v_lshlrev_b64 v[132:133], 11, v[132:133]
	v_lshl_add_u64 v[132:133], v[130:131], 0, v[132:133]
	global_load_dwordx4 v[184:187], v[132:133], off
	global_load_dwordx4 v[176:179], v[132:133], off offset:256
	v_or_b32_e32 v132, 32, v128
	v_ashrrev_i32_e32 v133, 31, v132
	v_lshlrev_b64 v[132:133], 11, v[132:133]
	v_lshl_add_u64 v[132:133], v[130:131], 0, v[132:133]
	global_load_dwordx4 v[172:175], v[132:133], off
	global_load_dwordx4 v[168:171], v[132:133], off offset:256
	v_or_b32_e32 v132, 48, v128
	v_ashrrev_i32_e32 v133, 31, v132
	v_lshlrev_b64 v[132:133], 11, v[132:133]
	v_lshl_add_u64 v[132:133], v[130:131], 0, v[132:133]
	global_load_dwordx4 v[164:167], v[132:133], off
	global_load_dwordx4 v[160:163], v[132:133], off offset:256
	v_add_u32_e32 v132, 0x80, v128
	v_ashrrev_i32_e32 v133, 31, v132
	v_lshlrev_b64 v[132:133], 11, v[132:133]
	v_lshl_add_u64 v[132:133], v[130:131], 0, v[132:133]
	global_load_dwordx4 v[156:159], v[132:133], off
	global_load_dwordx4 v[152:155], v[132:133], off offset:256
	v_add_u32_e32 v132, 0x90, v128
	v_ashrrev_i32_e32 v133, 31, v132
	v_lshlrev_b64 v[132:133], 11, v[132:133]
	v_lshl_add_u64 v[132:133], v[130:131], 0, v[132:133]
	global_load_dwordx4 v[148:151], v[132:133], off
	global_load_dwordx4 v[144:147], v[132:133], off offset:256
	v_add_u32_e32 v132, 0xa0, v128
	v_add_u32_e32 v128, 0xb0, v128
	v_ashrrev_i32_e32 v133, 31, v132
	v_ashrrev_i32_e32 v129, 31, v128
	v_lshlrev_b64 v[132:133], 11, v[132:133]
	v_lshlrev_b64 v[128:129], 11, v[128:129]
	v_lshl_add_u64 v[132:133], v[130:131], 0, v[132:133]
	v_lshl_add_u64 v[128:129], v[130:131], 0, v[128:129]
	global_load_dwordx4 v[140:143], v[132:133], off
	global_load_dwordx4 v[136:139], v[132:133], off offset:256
	s_nop 0
	global_load_dwordx4 v[132:135], v[128:129], off
	s_nop 0
	global_load_dwordx4 v[128:131], v[128:129], off offset:256
	v_and_b32_e32 v189, 64, v229
	v_xor_b32_e32 v188, 16, v229
	v_add_u32_e32 v190, 64, v189
	v_cmp_lt_i32_e32 vcc, v188, v190
	v_mul_f32_e32 v191, v127, v127
	v_fmac_f32_e32 v191, v126, v126
	v_cndmask_b32_e32 v188, v229, v188, vcc
	v_lshlrev_b32_e32 v189, 2, v188
	v_mul_f32_e32 v188, v125, v125
	v_fmac_f32_e32 v188, v124, v124
	v_add_f32_e32 v188, v188, v191
	v_mul_f32_e32 v191, v121, v121
	v_mul_f32_e32 v192, v123, v123
	v_fmac_f32_e32 v191, v120, v120
	v_fmac_f32_e32 v192, v122, v122
	v_add_f32_e32 v191, v191, v192
	v_add_f32_e32 v188, v188, v191
	v_mul_f32_e32 v191, v109, v109
	v_mul_f32_e32 v192, v111, v111
	v_fmac_f32_e32 v191, v108, v108
	v_fmac_f32_e32 v192, v110, v110
	v_add_f32_e32 v191, v191, v192
	v_add_f32_e32 v188, v188, v191
	v_mul_f32_e32 v191, v105, v105
	v_mul_f32_e32 v192, v107, v107
	v_fmac_f32_e32 v191, v104, v104
	v_fmac_f32_e32 v192, v106, v106
	v_add_f32_e32 v191, v191, v192
	v_add_f32_e32 v188, v188, v191
	v_mov_b32_e32 v191, v188
	s_nop 1
	v_permlane16_swap_b32_e32 v188, v191
	v_xor_b32_e32 v192, 32, v229
	v_cmp_lt_i32_e32 vcc, v192, v190
	s_lshl_b32 s0, s3, 2
	s_add_i32 s3, s0, 0
	v_cndmask_b32_e32 v190, v229, v192, vcc
	v_lshlrev_b32_e32 v190, 2, v190
	s_waitcnt lgkmcnt(0)
	v_add_f32_e32 v191, v188, v191
	v_mov_b32_e32 v192, v191
	s_nop 1
	v_permlane32_swap_b32_e32 v191, v192
	v_and_b32_e32 v188, 63, v182
	v_cmp_gt_u32_e32 vcc, 16, v188
	s_and_saveexec_b64 s[0:1], vcc
	s_cbranch_execz .LBB0_604
	s_lshl_b32 s10, s41, 10
	s_add_i32 s10, s3, s10
	v_lshl_add_u32 v193, v183, 4, s10
	s_waitcnt lgkmcnt(0)
	v_add_f32_e32 v191, v191, v192
	ds_write_b32 v193, v191
.LBB0_604:
	s_or_b64 exec, exec, s[0:1]
	v_mul_f32_e32 v191, v117, v117
	s_waitcnt lgkmcnt(0)
	v_mul_f32_e32 v192, v119, v119
	v_fmac_f32_e32 v191, v116, v116
	v_fmac_f32_e32 v192, v118, v118
	v_add_f32_e32 v191, v191, v192
	v_mul_f32_e32 v192, v113, v113
	v_mul_f32_e32 v193, v115, v115
	v_fmac_f32_e32 v192, v112, v112
	v_fmac_f32_e32 v193, v114, v114
	v_add_f32_e32 v192, v192, v193
	v_add_f32_e32 v191, v191, v192
	v_mul_f32_e32 v192, v101, v101
	v_mul_f32_e32 v193, v103, v103
	v_fmac_f32_e32 v192, v100, v100
	v_fmac_f32_e32 v193, v102, v102
	v_add_f32_e32 v192, v192, v193
	v_add_f32_e32 v191, v191, v192
	v_mul_f32_e32 v192, v97, v97
	v_mul_f32_e32 v193, v99, v99
	v_fmac_f32_e32 v192, v96, v96
	v_fmac_f32_e32 v193, v98, v98
	v_add_f32_e32 v192, v192, v193
	v_add_f32_e32 v191, v191, v192
	v_mov_b32_e32 v192, v191
	s_nop 1
	v_permlane16_swap_b32_e32 v191, v192
	s_waitcnt lgkmcnt(0)
	v_add_f32_e32 v191, v191, v192
	v_mov_b32_e32 v192, v191
	s_nop 1
	v_permlane32_swap_b32_e32 v191, v192
	s_and_saveexec_b64 s[0:1], vcc
	s_cbranch_execz .LBB0_606
	s_lshl_b32 s10, s41, 10
	s_add_i32 s10, s3, s10
	v_lshl_add_u32 v193, v183, 4, s10
	s_waitcnt lgkmcnt(0)
	v_add_f32_e32 v191, v191, v192
	ds_write_b32 v193, v191 offset:256
.LBB0_606:
	s_or_b64 exec, exec, s[0:1]
	v_mul_f32_e32 v191, v93, v93
	s_waitcnt lgkmcnt(0)
	v_mul_f32_e32 v192, v95, v95
	v_fmac_f32_e32 v191, v92, v92
	v_fmac_f32_e32 v192, v94, v94
	v_add_f32_e32 v191, v191, v192
	v_mul_f32_e32 v192, v89, v89
	v_mul_f32_e32 v193, v91, v91
	v_fmac_f32_e32 v192, v88, v88
	v_fmac_f32_e32 v193, v90, v90
	v_add_f32_e32 v192, v192, v193
	v_add_f32_e32 v191, v191, v192
	v_mul_f32_e32 v192, v85, v85
	v_mul_f32_e32 v193, v87, v87
	v_fmac_f32_e32 v192, v84, v84
	v_fmac_f32_e32 v193, v86, v86
	v_add_f32_e32 v192, v192, v193
	v_add_f32_e32 v191, v191, v192
	v_mul_f32_e32 v192, v77, v77
	v_mul_f32_e32 v193, v79, v79
	v_fmac_f32_e32 v192, v76, v76
	v_fmac_f32_e32 v193, v78, v78
	v_add_f32_e32 v192, v192, v193
	v_add_f32_e32 v191, v191, v192
	v_mov_b32_e32 v192, v191
	s_nop 1
	v_permlane16_swap_b32_e32 v191, v192
	s_waitcnt lgkmcnt(0)
	v_add_f32_e32 v191, v191, v192
	v_mov_b32_e32 v192, v191
	s_nop 1
	v_permlane32_swap_b32_e32 v191, v192
	s_and_saveexec_b64 s[0:1], vcc
	s_cbranch_execz .LBB0_608
	s_lshl_b32 s10, s41, 10
	s_add_i32 s10, s3, s10
	v_lshl_add_u32 v193, v183, 4, s10
	s_waitcnt lgkmcnt(0)
	v_add_f32_e32 v191, v191, v192
	ds_write_b32 v193, v191 offset:512
.LBB0_608:
	s_or_b64 exec, exec, s[0:1]
	v_mul_f32_e32 v191, v81, v81
	s_waitcnt lgkmcnt(0)
	v_mul_f32_e32 v192, v83, v83
	v_fmac_f32_e32 v191, v80, v80
	v_fmac_f32_e32 v192, v82, v82
	v_add_f32_e32 v191, v191, v192
	v_mul_f32_e32 v192, v73, v73
	v_mul_f32_e32 v193, v75, v75
	v_fmac_f32_e32 v192, v72, v72
	v_fmac_f32_e32 v193, v74, v74
	v_add_f32_e32 v192, v192, v193
	v_add_f32_e32 v191, v191, v192
	v_mul_f32_e32 v192, v69, v69
	v_mul_f32_e32 v193, v71, v71
	v_fmac_f32_e32 v192, v68, v68
	v_fmac_f32_e32 v193, v70, v70
	v_add_f32_e32 v192, v192, v193
	v_add_f32_e32 v191, v191, v192
	v_mul_f32_e32 v192, v65, v65
	v_mul_f32_e32 v193, v67, v67
	v_fmac_f32_e32 v192, v64, v64
	v_fmac_f32_e32 v193, v66, v66
	v_add_f32_e32 v192, v192, v193
	v_add_f32_e32 v191, v191, v192
	v_mov_b32_e32 v192, v191
	s_nop 1
	v_permlane16_swap_b32_e32 v191, v192
	s_waitcnt lgkmcnt(0)
	v_add_f32_e32 v191, v191, v192
	v_mov_b32_e32 v192, v191
	s_nop 1
	v_permlane32_swap_b32_e32 v191, v192
	s_and_saveexec_b64 s[0:1], vcc
	s_cbranch_execz .LBB0_610
	s_lshl_b32 s10, s41, 10
	s_add_i32 s10, s3, s10
	v_lshl_add_u32 v193, v183, 4, s10
	s_waitcnt lgkmcnt(0)
	v_add_f32_e32 v191, v191, v192
	ds_write_b32 v193, v191 offset:768
.LBB0_610:
	s_or_b64 exec, exec, s[0:1]
	v_mul_f32_e32 v191, v61, v61
	s_waitcnt lgkmcnt(0)
	v_mul_f32_e32 v192, v63, v63
	v_fmac_f32_e32 v191, v60, v60
	v_fmac_f32_e32 v192, v62, v62
	v_add_f32_e32 v191, v191, v192
	v_mul_f32_e32 v192, v57, v57
	v_mul_f32_e32 v193, v59, v59
	v_fmac_f32_e32 v192, v56, v56
	v_fmac_f32_e32 v193, v58, v58
	v_add_f32_e32 v192, v192, v193
	v_add_f32_e32 v191, v191, v192
	v_mul_f32_e32 v192, v53, v53
	v_mul_f32_e32 v193, v55, v55
	v_fmac_f32_e32 v192, v52, v52
	v_fmac_f32_e32 v193, v54, v54
	v_add_f32_e32 v192, v192, v193
	v_add_f32_e32 v191, v191, v192
	v_mul_f32_e32 v192, v45, v45
	v_mul_f32_e32 v193, v47, v47
	v_fmac_f32_e32 v192, v44, v44
	v_fmac_f32_e32 v193, v46, v46
	v_add_f32_e32 v192, v192, v193
	v_add_f32_e32 v191, v191, v192
	v_mov_b32_e32 v192, v191
	s_nop 1
	v_permlane16_swap_b32_e32 v191, v192
	s_waitcnt lgkmcnt(0)
	v_add_f32_e32 v191, v191, v192
	v_mov_b32_e32 v192, v191
	s_nop 1
	v_permlane32_swap_b32_e32 v191, v192
	s_and_saveexec_b64 s[0:1], vcc
	s_cbranch_execz .LBB0_612
	s_lshl_b32 s10, s41, 10
	s_add_i32 s10, s3, s10
	v_lshl_add_u32 v193, v183, 4, s10
	s_waitcnt lgkmcnt(0)
	v_add_f32_e32 v191, v191, v192
	ds_write_b32 v193, v191 offset:2048
.LBB0_612:
	s_or_b64 exec, exec, s[0:1]
	v_mul_f32_e32 v191, v49, v49
	s_waitcnt lgkmcnt(0)
	v_mul_f32_e32 v192, v51, v51
	v_fmac_f32_e32 v191, v48, v48
	v_fmac_f32_e32 v192, v50, v50
	v_add_f32_e32 v191, v191, v192
	v_mul_f32_e32 v192, v41, v41
	v_mul_f32_e32 v193, v43, v43
	v_fmac_f32_e32 v192, v40, v40
	v_fmac_f32_e32 v193, v42, v42
	v_add_f32_e32 v192, v192, v193
	v_add_f32_e32 v191, v191, v192
	v_mul_f32_e32 v192, v37, v37
	v_mul_f32_e32 v193, v39, v39
	v_fmac_f32_e32 v192, v36, v36
	v_fmac_f32_e32 v193, v38, v38
	v_add_f32_e32 v192, v192, v193
	v_add_f32_e32 v191, v191, v192
	v_mul_f32_e32 v192, v33, v33
	v_mul_f32_e32 v193, v35, v35
	v_fmac_f32_e32 v192, v32, v32
	v_fmac_f32_e32 v193, v34, v34
	v_add_f32_e32 v192, v192, v193
	v_add_f32_e32 v191, v191, v192
	v_mov_b32_e32 v192, v191
	s_nop 1
	v_permlane16_swap_b32_e32 v191, v192
	s_waitcnt lgkmcnt(0)
	v_add_f32_e32 v191, v191, v192
	v_mov_b32_e32 v192, v191
	s_nop 1
	v_permlane32_swap_b32_e32 v191, v192
	s_and_saveexec_b64 s[0:1], vcc
	s_cbranch_execz .LBB0_614
	s_lshl_b32 s10, s41, 10
	s_add_i32 s10, s3, s10
	v_lshl_add_u32 v193, v183, 4, s10
	s_waitcnt lgkmcnt(0)
	v_add_f32_e32 v191, v191, v192
	ds_write_b32 v193, v191 offset:2304
.LBB0_614:
	s_or_b64 exec, exec, s[0:1]
	v_mul_f32_e32 v191, v29, v29
	s_waitcnt lgkmcnt(0)
	v_mul_f32_e32 v192, v31, v31
	v_fmac_f32_e32 v191, v28, v28
	v_fmac_f32_e32 v192, v30, v30
	v_add_f32_e32 v191, v191, v192
	v_mul_f32_e32 v192, v25, v25
	v_mul_f32_e32 v193, v27, v27
	v_fmac_f32_e32 v192, v24, v24
	v_fmac_f32_e32 v193, v26, v26
	v_add_f32_e32 v192, v192, v193
	v_add_f32_e32 v191, v191, v192
	v_mul_f32_e32 v192, v21, v21
	v_mul_f32_e32 v193, v23, v23
	v_fmac_f32_e32 v192, v20, v20
	v_fmac_f32_e32 v193, v22, v22
	v_add_f32_e32 v192, v192, v193
	v_add_f32_e32 v191, v191, v192
	v_mul_f32_e32 v192, v13, v13
	v_mul_f32_e32 v193, v15, v15
	v_fmac_f32_e32 v192, v12, v12
	v_fmac_f32_e32 v193, v14, v14
	v_add_f32_e32 v192, v192, v193
	v_add_f32_e32 v191, v191, v192
	v_mov_b32_e32 v192, v191
	s_nop 1
	v_permlane16_swap_b32_e32 v191, v192
	s_waitcnt lgkmcnt(0)
	v_add_f32_e32 v191, v191, v192
	v_mov_b32_e32 v192, v191
	s_nop 1
	v_permlane32_swap_b32_e32 v191, v192
	s_and_saveexec_b64 s[0:1], vcc
	s_cbranch_execz .LBB0_616
	s_lshl_b32 s10, s41, 10
	s_add_i32 s10, s3, s10
	v_lshl_add_u32 v193, v183, 4, s10
	s_waitcnt lgkmcnt(0)
	v_add_f32_e32 v191, v191, v192
	ds_write_b32 v193, v191 offset:2560
.LBB0_616:
	s_or_b64 exec, exec, s[0:1]
	v_mul_f32_e32 v191, v17, v17
	s_waitcnt lgkmcnt(0)
	v_mul_f32_e32 v192, v19, v19
	v_fmac_f32_e32 v191, v16, v16
	v_fmac_f32_e32 v192, v18, v18
	v_add_f32_e32 v191, v191, v192
	v_mul_f32_e32 v192, v9, v9
	v_mul_f32_e32 v193, v11, v11
	v_fmac_f32_e32 v192, v8, v8
	v_fmac_f32_e32 v193, v10, v10
	v_add_f32_e32 v192, v192, v193
	v_add_f32_e32 v191, v191, v192
	v_mul_f32_e32 v192, v5, v5
	v_mul_f32_e32 v193, v7, v7
	v_fmac_f32_e32 v192, v4, v4
	v_fmac_f32_e32 v193, v6, v6
	v_add_f32_e32 v192, v192, v193
	v_add_f32_e32 v191, v191, v192
	v_mul_f32_e32 v192, v1, v1
	v_mul_f32_e32 v193, v3, v3
	v_fmac_f32_e32 v192, v0, v0
	v_fmac_f32_e32 v193, v2, v2
	v_add_f32_e32 v192, v192, v193
	v_add_f32_e32 v191, v191, v192
	v_mov_b32_e32 v189, v191
	s_nop 1
	v_permlane16_swap_b32_e32 v191, v189
	s_waitcnt lgkmcnt(0)
	v_add_f32_e32 v189, v191, v189
	v_mov_b32_e32 v190, v189
	s_nop 1
	v_permlane32_swap_b32_e32 v189, v190
	s_and_saveexec_b64 s[0:1], vcc
	s_cbranch_execz .LBB0_618
	s_lshl_b32 s10, s41, 10
	s_add_i32 s3, s3, s10
	v_lshl_add_u32 v183, v183, 4, s3
	s_waitcnt lgkmcnt(0)
	v_add_f32_e32 v189, v189, v190
	ds_write_b32 v183, v189 offset:2816
